# ret2 and fft2 units: the early counter read no longer waits before the unit's independent loads are issued (wait moved behind them); plus attention mask-skip
# baseline (speedup 1.0000x reference)
.LBB0_675:
	s_cmp_gt_u32 s9, 63
	s_mov_b64 s[6:7], -1
	s_cbranch_scc0 .LBB0_713
	s_cmpk_gt_u32 s9, 0x13f
	s_cbranch_scc0 .LBB0_696
	s_add_i32 s0, s9, 0xfffffec0
	s_mul_hi_u32 s6, s0, 0xf0f0f0f1
	s_lshr_b32 s8, s6, 5
	s_mul_i32 s6, s8, 34
	s_sub_i32 s21, s0, s6
	s_cmp_gt_u32 s21, 1
	v_readlane_b32 s12, v254, 48
	s_cselect_b64 s[6:7], -1, 0
	v_readlane_b32 s13, v254, 49
	s_or_b64 s[6:7], s[12:13], s[6:7]
	s_andn2_b64 vcc, exec, s[6:7]
	s_cbranch_vccnz .LBB0_695
	s_and_b32 s20, s8, 3
	s_lshl_b32 s6, s5, 3
	s_or_b32 s6, s20, s6
	s_ashr_i32 s7, s6, 31
	s_lshl_b64 s[6:7], s[6:7], 2
	s_add_u32 s6, s42, s6
	s_addc_u32 s7, s43, s7
	global_load_dword v27, v33, s[6:7]
	global_load_dword v26, v33, s[6:7] offset:16
	s_lshl_b32 s6, s5, 4
	s_and_b32 s7, s8, 0x3fffffc
	s_add_i32 s7, s7, s6
	s_or_b32 s6, s7, s20
	s_lshl_b32 s6, s6, 4
	s_ashr_i32 s7, s6, 31
	s_lshl_b64 s[6:7], s[6:7], 2
	v_readlane_b32 s12, v254, 63
	s_add_u32 s12, s12, s6
	v_readlane_b32 s6, v255, 0
	s_addc_u32 s13, s6, s7
	v_cmp_eq_u32_e64 s[6:7], 0, v206
	s_mov_b64 s[16:17], -1
	s_and_saveexec_b64 s[18:19], s[6:7]
	s_cbranch_execz .LBB0_680
	global_load_dword v236, v33, s[12:13] sc1
.LBB0_680:
	s_or_b64 exec, exec, s[18:19]
	s_lshr_b32 s8, s8, 2
	s_lshl_b32 s18, s21, 7
	s_cmp_lt_u32 s21, 2
	s_movk_i32 s21, 0xff00
	s_cselect_b32 s19, 8, 12
	s_cselect_b32 s21, 0x4000, s21
	s_lshl_b32 s8, s8, s19
	s_add_i32 s18, s21, s18
	s_add_i32 s8, s18, s8
	s_lshl_b32 s92, s20, 7
	v_lshlrev_b32_e32 v24, 3, v206
	v_ashrrev_i32_e32 v43, 3, v206
	s_add_u32 s18, s70, s92
	v_and_b32_e32 v40, 56, v24
	v_add_u32_e32 v2, s8, v43
	v_add_u32_e32 v25, 0x200, v206
	s_addc_u32 s19, s71, 0
	v_lshlrev_b32_e32 v32, 1, v40
	v_ashrrev_i32_e32 v3, 31, v2
	v_ashrrev_i32_e32 v42, 3, v25
	v_lshl_add_u64 v[0:1], s[18:19], 0, v[32:33]
	v_lshlrev_b64 v[2:3], 13, v[2:3]
	v_add_u32_e32 v4, s8, v42
	v_lshl_add_u64 v[2:3], v[0:1], 0, v[2:3]
	s_movk_i32 s18, 0x1000
	v_ashrrev_i32_e32 v5, 31, v4
	v_add_co_u32_e32 v2, vcc, s18, v2
	v_lshlrev_b64 v[4:5], 13, v[4:5]
	s_nop 0
	v_addc_co_u32_e32 v3, vcc, 0, v3, vcc
	v_lshl_add_u64 v[0:1], v[0:1], 0, v[4:5]
	v_add_co_u32_e32 v0, vcc, s18, v0
	v_readlane_b32 s18, v254, 52
	v_and_b32_e32 v37, 15, v206
	s_add_i32 s18, s8, s18
	v_or_b32_e32 v28, s18, v37
	v_ashrrev_i32_e32 v29, 31, v28
	v_lshlrev_b64 v[28:29], 13, v[28:29]
	v_lshrrev_b32_e32 v41, 4, v207
	v_lshl_add_u64 v[28:29], s[70:71], 0, v[28:29]
	v_lshl_add_u64 v[28:29], v[28:29], 0, s[92:93]
	v_lshlrev_b32_e32 v38, 3, v41
	v_mov_b32_e32 v39, v33
	v_addc_co_u32_e32 v1, vcc, 0, v1, vcc
	v_lshl_add_u64 v[28:29], v[28:29], 0, v[38:39]
	s_mov_b64 s[18:19], 0x1800
	v_lshl_add_u64 v[30:31], v[28:29], 0, s[18:19]
	v_add_co_u32_e32 v28, vcc, 0x1000, v28
	global_load_dwordx4 v[16:19], v[2:3], off offset:512
	global_load_dwordx4 v[20:23], v[2:3], off offset:1024
	v_addc_co_u32_e32 v29, vcc, 0, v29, vcc
	global_load_dwordx4 v[8:11], v[2:3], off offset:1536
	global_load_dwordx4 v[4:7], v[0:1], off offset:512
	global_load_dwordx4 v[12:15], v[0:1], off offset:1024
	s_nop 0
	global_load_dwordx4 v[0:3], v[0:1], off offset:1536
	s_nop 0
	global_load_dwordx2 v[66:67], v[28:29], off offset:2048
	global_load_dwordx2 v[64:65], v[30:31], off offset:32
	global_load_dwordx2 v[62:63], v[30:31], off offset:64
	global_load_dwordx2 v[34:35], v[30:31], off offset:96
	s_and_saveexec_b64 s[100:101], s[6:7]
	s_cbranch_execz .Lr2p_skip
	s_waitcnt vmcnt(10)
	v_cmp_gt_u32_e32 vcc, 4, v236
	s_orn2_b64 s[16:17], vcc, exec
.Lr2p_skip:
	s_or_b64 exec, exec, s[100:101]
	s_and_b64 s[16:17], s[6:7], s[16:17]
	s_and_saveexec_b64 s[6:7], s[16:17]
	s_cbranch_execz .LBB0_692
	global_load_dword v28, v33, s[12:13] sc1
	s_waitcnt vmcnt(0)
	v_cmp_lt_u32_e32 vcc, 3, v28
	s_cbranch_vccnz .LBB0_692
	s_mov_b32 s18, 0x3ffff8
	s_branch .LBB0_684

.LBB0_696:
	s_andn2_b64 vcc, exec, s[6:7]
	s_cbranch_vccnz .LBB0_712
	s_sub_i32 s8, s9, 64
	s_lshr_b32 s0, s8, 6
	s_lshl_b32 s6, s5, 6
	s_lshl_b32 s7, s0, 4
	s_add_i32 s6, s7, s6
	s_ashr_i32 s7, s6, 31
	s_lshl_b64 s[6:7], s[6:7], 2
	v_readlane_b32 s12, v255, 1
	s_add_u32 s12, s12, s6
	v_readlane_b32 s6, v255, 2
	s_addc_u32 s13, s6, s7
	v_cmp_eq_u32_e64 s[6:7], 0, v206
	s_mov_b64 s[16:17], -1
	s_and_saveexec_b64 s[18:19], s[6:7]
	s_cbranch_execz .LBB0_699
	global_load_dword v236, v33, s[12:13] sc1
.LBB0_699:
	s_or_b64 exec, exec, s[18:19]
	v_lshlrev_b32_e32 v0, 3, v206
	v_and_b32_e32 v16, 0xf8, v0
	v_lshlrev_b32_e32 v0, 1, v206
	s_mulk_i32 s0, 0xfc0
	s_add_i32 s0, s0, s8
	v_and_b32_e32 v0, 0xffffffc0, v0
	v_add_u32_e32 v0, s0, v0
	v_ashrrev_i32_e32 v1, 31, v0
	v_lshlrev_b64 v[2:3], 13, v[0:1]
	v_add_u32_e32 v4, 0x400, v0
	v_lshl_add_u64 v[2:3], s[48:49], 0, v[2:3]
	v_lshlrev_b32_e32 v32, 1, v16
	v_ashrrev_i32_e32 v5, 31, v4
	v_lshl_add_u64 v[2:3], v[2:3], 0, v[32:33]
	s_mov_b32 s18, 0x7c01000
	v_lshlrev_b64 v[4:5], 13, v[4:5]
	v_add_co_u32_e32 v2, vcc, s18, v2
	v_lshl_add_u64 v[4:5], s[48:49], 0, v[4:5]
	s_nop 0
	v_addc_co_u32_e32 v3, vcc, 0, v3, vcc
	v_lshl_add_u64 v[4:5], v[4:5], 0, v[32:33]
	v_add_co_u32_e32 v4, vcc, s18, v4
	s_nop 0
	v_addc_co_u32_e32 v5, vcc, 0, v5, vcc
	global_load_dwordx4 v[12:15], v[2:3], off offset:3584
	global_load_dwordx4 v[8:11], v[4:5], off offset:3584
	v_add_u32_e32 v2, 0x800, v0
	v_ashrrev_i32_e32 v3, 31, v2
	v_lshlrev_b64 v[2:3], 13, v[2:3]
	v_add_u32_e32 v0, 0xc00, v0
	v_lshl_add_u64 v[2:3], s[48:49], 0, v[2:3]
	v_ashrrev_i32_e32 v1, 31, v0
	v_lshl_add_u64 v[2:3], v[2:3], 0, v[32:33]
	v_lshlrev_b64 v[0:1], 13, v[0:1]
	v_add_co_u32_e32 v2, vcc, s18, v2
	v_lshl_add_u64 v[0:1], s[48:49], 0, v[0:1]
	s_nop 0
	v_addc_co_u32_e32 v3, vcc, 0, v3, vcc
	v_lshl_add_u64 v[0:1], v[0:1], 0, v[32:33]
	v_add_co_u32_e32 v0, vcc, 0x7c01000, v0
	s_nop 1
	v_addc_co_u32_e32 v1, vcc, 0, v1, vcc
	global_load_dwordx4 v[4:7], v[2:3], off offset:3584
	s_nop 0
	global_load_dwordx4 v[0:3], v[0:1], off offset:3584
	s_and_saveexec_b64 s[100:101], s[6:7]
	s_cbranch_execz .Lf2p_skip
	s_waitcnt vmcnt(4)
	v_cmp_gt_u32_e32 vcc, 64, v236
	s_orn2_b64 s[16:17], vcc, exec
.Lf2p_skip:
	s_or_b64 exec, exec, s[100:101]
	s_and_b64 s[16:17], s[6:7], s[16:17]
	s_and_saveexec_b64 s[6:7], s[16:17]
	s_cbranch_execz .LBB0_711
	global_load_dword v17, v33, s[12:13] sc1
	s_waitcnt vmcnt(0)
	v_cmp_lt_u32_e32 vcc, 63, v17
	s_cbranch_vccnz .LBB0_711
	s_mov_b32 s18, 0x3ffff8
	s_branch .LBB0_703
